# HGRN scan: deferred transposed quad reduction (12 cndmask + 6 dpp per 4 steps instead of 16 dpp + 6 cndmask + nops)
# baseline (speedup 1.0000x reference)
; #define HG_LD(X, tl_) do { const float* f_ = sF + (tl_) * 128 + seg * 4; const float* q_ = sQ + (tl_) * 128 + seg * 4;   \
;                 X##f0 = *(const f32x4*)(f_); X##f1 = *(const f32x4*)(f_ + 64); X##q0 = *(const f32x4*)(q_); X##q1 = *(const f32x4*)(q_ + 64); \
;                 X##va = sDV[(tl_) * 64 + cp]; X##vb = sDV[(tl_) * 64 + 32 + cp]; } while (0)
; __device__ __forceinline__ void phase_hgrn(KP P, int l_, unsigned char* shm) {
;     ...
;             {
;                 f32x4 Af0, Af1, Aq0, Aq1; float Ava, Avb;
;                 f32x4 Bf0, Bf1, Bq0, Bq1; float Bva, Bvb;
;                 HG_LD(A, 0);
.LBB0_2162:
	ds_read_b128 v[18:21], v111
	ds_read_b128 v[14:17], v111 offset:256
	ds_read_b128 v[10:13], v111 offset:16384
	ds_read_b128 v[6:9], v111 offset:16640
	ds_read2_b32 v[78:79], v116 offset1:32
	s_mov_b32 s17, -2
	v_mov_b32_e32 v129, v110
	v_mov_b32_e32 v130, v109
	v_and_b32_e32 v133, 3, v228
	v_mul_u32_u24_e32 v133, 0x3ff, v133
	v_add_u32_e32 v135, v107, v133
	v_add_u32_e32 v136, v108, v133
	s_mov_b32 s60, 0xaaaaaaaa
	s_mov_b32 s61, 0xaaaaaaaa
	s_mov_b32 s62, 0xcccccccc
	s_mov_b32 s63, 0xcccccccc
	s_waitcnt lgkmcnt(0)
	s_branch .LBB0_2164

; #define HG_LD(X, tl_) do { const float* f_ = sF + (tl_) * 128 + seg * 4; const float* q_ = sQ + (tl_) * 128 + seg * 4;   \
;                 X##f0 = *(const f32x4*)(f_); X##f1 = *(const f32x4*)(f_ + 64); X##q0 = *(const f32x4*)(q_); X##q1 = *(const f32x4*)(q_ + 64); \
;                 X##va = sDV[(tl_) * 64 + cp]; X##vb = sDV[(tl_) * 64 + 32 + cp]; } while (0)
; __device__ __forceinline__ void phase_hgrn(KP P, int l_, unsigned char* shm) {
;     ...
;                 for (int tl = 0; tl < T; tl += 2) {
;                     HG_LD(B, tl + 1);
;                     HG_STEP(A, tl);
;                     HG_LD(A, tl + 2);
;                     HG_STEP(B, tl + 1);
;                 }
.LBB0_2164:
	ds_read_b128 v[34:37], v129
	ds_read_b128 v[30:33], v129 offset:256
	ds_read_b128 v[26:29], v129 offset:16384
	ds_read_b128 v[22:25], v129 offset:16640
	ds_read2_b32 v[80:81], v130 offset1:32
	s_waitcnt lgkmcnt(8)
	v_pk_fma_f32 v[70:71], v[20:21], v[70:71], v[78:79] op_sel_hi:[1,1,0]
	v_pk_fma_f32 v[76:77], v[20:21], v[76:77], v[78:79] op_sel:[0,0,1]
	v_pk_fma_f32 v[64:65], v[18:19], v[64:65], v[78:79] op_sel_hi:[1,1,0]
	v_pk_fma_f32 v[82:83], v[18:19], v[62:63], v[78:79] op_sel:[0,0,1]
	s_waitcnt lgkmcnt(7)
	v_pk_fma_f32 v[68:69], v[14:15], v[68:69], v[78:79] op_sel_hi:[1,1,0]
	v_pk_fma_f32 v[74:75], v[14:15], v[74:75], v[78:79] op_sel:[0,0,1]
	v_pk_fma_f32 v[66:67], v[16:17], v[66:67], v[78:79] op_sel_hi:[1,1,0]
	v_pk_fma_f32 v[72:73], v[16:17], v[72:73], v[78:79] op_sel:[0,0,1]
	v_pk_mul_f32 v[14:15], v[12:13], v[70:71]
	v_pk_mul_f32 v[12:13], v[12:13], v[76:77]
	v_pk_fma_f32 v[14:15], v[10:11], v[64:65], v[14:15]
	v_pk_fma_f32 v[10:11], v[10:11], v[82:83], v[12:13]
	v_pk_fma_f32 v[12:13], v[8:9], v[66:67], v[14:15]
	v_pk_fma_f32 v[8:9], v[8:9], v[72:73], v[10:11]
	v_pk_fma_f32 v[12:13], v[6:7], v[68:69], v[12:13]
	v_pk_fma_f32 v[6:7], v[6:7], v[74:75], v[8:9]
	v_add_f32_e32 v137, v12, v13
	v_add_f32_e32 v141, v6, v7
	s_waitcnt lgkmcnt(0)
	ds_read_b128 v[18:21], v129 offset:512
	ds_read_b128 v[14:17], v129 offset:768
	ds_read_b128 v[10:13], v129 offset:16896
	ds_read_b128 v[6:9], v129 offset:17152
	ds_read2_b32 v[62:63], v130 offset0:64 offset1:96
	v_pk_fma_f32 v[70:71], v[70:71], v[36:37], v[80:81] op_sel_hi:[1,1,0]
	v_pk_fma_f32 v[76:77], v[36:37], v[76:77], v[80:81] op_sel:[0,0,1]
	v_pk_fma_f32 v[64:65], v[64:65], v[34:35], v[80:81] op_sel_hi:[1,1,0]
	v_pk_fma_f32 v[78:79], v[34:35], v[82:83], v[80:81] op_sel:[0,0,1]
	v_pk_fma_f32 v[82:83], v[68:69], v[30:31], v[80:81] op_sel_hi:[1,1,0]
	v_pk_fma_f32 v[84:85], v[74:75], v[30:31], v[80:81] op_sel:[0,0,1]
	v_pk_fma_f32 v[86:87], v[66:67], v[32:33], v[80:81] op_sel_hi:[1,1,0]
	v_pk_fma_f32 v[88:89], v[72:73], v[32:33], v[80:81] op_sel:[0,0,1]
	v_pk_mul_f32 v[30:31], v[28:29], v[70:71]
	v_pk_mul_f32 v[28:29], v[28:29], v[76:77]
	v_pk_fma_f32 v[30:31], v[26:27], v[64:65], v[30:31]
	v_pk_fma_f32 v[26:27], v[26:27], v[78:79], v[28:29]
	v_pk_fma_f32 v[28:29], v[24:25], v[86:87], v[30:31]
	v_pk_fma_f32 v[24:25], v[24:25], v[88:89], v[26:27]
	v_pk_fma_f32 v[28:29], v[22:23], v[82:83], v[28:29]
	v_pk_fma_f32 v[22:23], v[22:23], v[84:85], v[24:25]
	v_add_f32_e32 v138, v28, v29
	v_add_f32_e32 v142, v22, v23
	s_waitcnt lgkmcnt(0)
	ds_read_b128 v[34:37], v129 offset:1024
	ds_read_b128 v[30:33], v129 offset:1280
	ds_read_b128 v[26:29], v129 offset:17408
	ds_read_b128 v[22:25], v129 offset:17664
	ds_read2_b32 v[66:67], v130 offset0:128 offset1:160
	v_pk_fma_f32 v[70:71], v[20:21], v[70:71], v[62:63] op_sel_hi:[1,1,0]
	v_pk_fma_f32 v[72:73], v[20:21], v[76:77], v[62:63] op_sel:[0,0,1]
	v_pk_fma_f32 v[64:65], v[18:19], v[64:65], v[62:63] op_sel_hi:[1,1,0]
	v_pk_fma_f32 v[68:69], v[18:19], v[78:79], v[62:63] op_sel:[0,0,1]
	v_pk_fma_f32 v[74:75], v[14:15], v[82:83], v[62:63] op_sel_hi:[1,1,0]
	v_pk_fma_f32 v[80:81], v[14:15], v[84:85], v[62:63] op_sel:[0,0,1]
	v_pk_fma_f32 v[82:83], v[16:17], v[86:87], v[62:63] op_sel_hi:[1,1,0]
	v_pk_fma_f32 v[84:85], v[16:17], v[88:89], v[62:63] op_sel:[0,0,1]
	v_pk_mul_f32 v[14:15], v[12:13], v[70:71]
	v_pk_mul_f32 v[12:13], v[12:13], v[72:73]
	v_pk_fma_f32 v[14:15], v[10:11], v[64:65], v[14:15]
	v_pk_fma_f32 v[10:11], v[10:11], v[68:69], v[12:13]
	v_pk_fma_f32 v[12:13], v[8:9], v[82:83], v[14:15]
	v_pk_fma_f32 v[8:9], v[8:9], v[84:85], v[10:11]
	v_pk_fma_f32 v[12:13], v[6:7], v[74:75], v[12:13]
	v_pk_fma_f32 v[6:7], v[6:7], v[80:81], v[8:9]
	v_add_f32_e32 v139, v12, v13
	v_add_f32_e32 v143, v6, v7
	s_waitcnt lgkmcnt(0)
	v_pk_fma_f32 v[70:71], v[70:71], v[36:37], v[66:67] op_sel_hi:[1,1,0]
	v_pk_fma_f32 v[76:77], v[36:37], v[72:73], v[66:67] op_sel:[0,0,1]
	v_pk_fma_f32 v[64:65], v[64:65], v[34:35], v[66:67] op_sel_hi:[1,1,0]
	v_pk_fma_f32 v[62:63], v[34:35], v[68:69], v[66:67] op_sel:[0,0,1]
	v_pk_fma_f32 v[68:69], v[74:75], v[30:31], v[66:67] op_sel_hi:[1,1,0]
	v_pk_fma_f32 v[74:75], v[80:81], v[30:31], v[66:67] op_sel:[0,0,1]
	v_pk_fma_f32 v[72:73], v[84:85], v[32:33], v[66:67] op_sel:[0,0,1]
	v_pk_fma_f32 v[66:67], v[82:83], v[32:33], v[66:67] op_sel_hi:[1,1,0]
	v_pk_mul_f32 v[30:31], v[28:29], v[70:71]
	v_pk_mul_f32 v[28:29], v[28:29], v[76:77]
	v_pk_fma_f32 v[30:31], v[26:27], v[64:65], v[30:31]
	v_pk_fma_f32 v[26:27], v[26:27], v[62:63], v[28:29]
	v_pk_fma_f32 v[28:29], v[24:25], v[66:67], v[30:31]
	v_pk_fma_f32 v[24:25], v[24:25], v[72:73], v[26:27]
	v_pk_fma_f32 v[28:29], v[22:23], v[68:69], v[28:29]
	v_pk_fma_f32 v[22:23], v[22:23], v[74:75], v[24:25]
	v_add_f32_e32 v140, v28, v29
	v_add_f32_e32 v144, v22, v23
	ds_read2_b32 v[78:79], v130 offset0:192 offset1:224
	ds_read_b128 v[18:21], v129 offset:1536
	ds_read_b128 v[14:17], v129 offset:1792
	ds_read_b128 v[10:13], v129 offset:17920
	ds_read_b128 v[6:9], v129 offset:18176
	v_cndmask_b32_e64 v145, v137, v138, s[60:61]
	v_cndmask_b32_e64 v146, v138, v137, s[60:61]
	v_cndmask_b32_e64 v147, v139, v140, s[60:61]
	v_cndmask_b32_e64 v148, v140, v139, s[60:61]
	v_cndmask_b32_e64 v149, v141, v142, s[60:61]
	v_cndmask_b32_e64 v150, v142, v141, s[60:61]
	v_cndmask_b32_e64 v151, v143, v144, s[60:61]
	v_cndmask_b32_e64 v152, v144, v143, s[60:61]
	v_add_f32_dpp v145, v146, v145 quad_perm:[1,0,3,2] row_mask:0xf bank_mask:0xf bound_ctrl:1
	v_add_f32_dpp v147, v148, v147 quad_perm:[1,0,3,2] row_mask:0xf bank_mask:0xf bound_ctrl:1
	v_add_f32_dpp v149, v150, v149 quad_perm:[1,0,3,2] row_mask:0xf bank_mask:0xf bound_ctrl:1
	v_add_f32_dpp v151, v152, v151 quad_perm:[1,0,3,2] row_mask:0xf bank_mask:0xf bound_ctrl:1
	v_cndmask_b32_e64 v146, v147, v145, s[62:63]
	v_cndmask_b32_e64 v148, v151, v149, s[62:63]
	v_cndmask_b32_e64 v133, v145, v147, s[62:63]
	v_cndmask_b32_e64 v134, v149, v151, s[62:63]
	v_add_f32_dpp v133, v146, v133 quad_perm:[2,3,0,1] row_mask:0xf bank_mask:0xf bound_ctrl:1
	v_add_f32_dpp v134, v148, v134 quad_perm:[2,3,0,1] row_mask:0xf bank_mask:0xf bound_ctrl:1
	ds_write_b32 v135, v133
	ds_write_b32 v136, v134
	s_branch .LBB0_2163
